# combined: static serpentine attention schedule + attention epilogue gate-load hoist + running prefetch pointers + FFN-in row-interleaved conv
# speedup vs baseline: 1.0158x; 1.0108x over previous
.LBB0_790:
	s_waitcnt vmcnt(0)
	s_barrier
	v_readfirstlane_b32 s100, v235
	s_nop 3
	s_mul_i32 s101, s100, s42
	s_sub_i32 s0, s42, 1
	s_sub_i32 s0, s0, s2
	s_bitcmp0_b32 s100, 0
	s_cselect_b32 s0, s2, s0
	s_add_i32 s101, s101, s0
	v_add_u32_e32 v235, 1, v235
	v_mov_b32_e32 v0, s101
	s_movk_i32 s0, 0x480
	s_mov_b64 s[8:9], -1
	v_cmp_gt_i32_e64 s[6:7], s0, v0
	s_and_saveexec_b64 s[68:69], s[6:7]
	s_cbranch_execz .LBB0_789
	v_ashrrev_i32_e32 v1, 31, v0
	v_lshrrev_b32_e32 v1, 25, v1
	v_add_u32_e32 v1, v0, v1
	v_ashrrev_i32_e32 v8, 7, v1
	v_and_b32_e32 v1, 0xffffff80, v1
	v_sub_u32_e32 v0, v0, v1
	v_mov_b32_e32 v1, 11
	v_lshrrev_b16_sdwa v1, v1, sext(v0) dst_sel:DWORD dst_unused:UNUSED_PAD src0_sel:DWORD src1_sel:BYTE_0
	v_and_b32_e32 v1, 15, v1
	v_add_u16_e32 v1, v0, v1
	v_sub_u32_e32 v9, 8, v8
	v_ashrrev_i16_sdwa v2, v198, sext(v1) dst_sel:DWORD dst_unused:UNUSED_PAD src0_sel:DWORD src1_sel:BYTE_0
	s_movk_i32 s0, 0x810
	v_and_b32_e32 v1, 0xf0, v1
	v_mul_hi_i32_i24_sdwa v135, sext(v2), s0 dst_sel:DWORD dst_unused:UNUSED_PAD src0_sel:WORD_0 src1_sel:DWORD
	v_mul_i32_i24_sdwa v134, sext(v2), s0 dst_sel:DWORD dst_unused:UNUSED_PAD src0_sel:WORD_0 src1_sel:DWORD
	v_mul_hi_i32_i24_e32 v3, 0x2040, v0
	v_mul_i32_i24_e32 v2, 0x2040, v0
	v_lshlrev_b32_e32 v10, 8, v9
	v_sub_u16_e32 v4, v0, v1
	v_lshl_add_u64 v[140:141], s[62:63], 0, v[2:3]
	v_add_u32_e32 v164, v10, v156
	v_mov_b32_e32 v2, 6
	v_lshlrev_b32_sdwa v138, v2, sext(v4) dst_sel:DWORD dst_unused:UNUSED_PAD src0_sel:DWORD src1_sel:BYTE_0
	v_max_i32_e32 v6, 0xf0, v164
	v_ashrrev_i32_e32 v139, 31, v138
	v_add_u32_e32 v172, 0xffffff10, v6
	v_lshlrev_b64 v[2:3], 1, v[138:139]
	v_lshl_add_u64 v[6:7], v[134:135], 0, v[172:173]
	v_lshl_add_u64 v[4:5], v[120:121], 0, v[2:3]
	v_lshlrev_b64 v[6:7], 12, v[6:7]
	v_lshl_add_u64 v[6:7], v[4:5], 0, v[6:7]
	v_or_b32_e32 v139, 16, v164
	global_load_dwordx4 v[20:23], v[6:7], off
	global_load_dwordx4 v[24:27], v[6:7], off offset:64
	v_max_i32_e32 v6, 0xf0, v139
	v_add_u32_e32 v172, 0xffffff10, v6
	v_lshl_add_u64 v[6:7], v[134:135], 0, v[172:173]
	v_lshlrev_b64 v[6:7], 12, v[6:7]
	v_ashrrev_i32_e32 v1, 31, v0
	v_lshl_add_u64 v[4:5], v[4:5], 0, v[6:7]
	global_load_dwordx4 v[28:31], v[4:5], off
	global_load_dwordx4 v[32:35], v[4:5], off offset:64
	v_lshl_add_u64 v[4:5], v[134:135], 0, v[124:125]
	v_lshlrev_b64 v[0:1], 6, v[0:1]
	v_lshlrev_b64 v[4:5], 11, v[4:5]
	v_lshl_add_u64 v[0:1], v[0:1], 0, v[122:123]
	v_mov_b64_e32 v[6:7], s[88:89]
	v_lshl_add_u64 v[4:5], s[70:71], 0, v[4:5]
	v_mad_u64_u32 v[144:145], s[6:7], v0, s52, v[6:7]
	v_lshl_add_u64 v[4:5], v[4:5], 0, v[2:3]
	v_lshlrev_b32_e32 v142, 1, v126
	v_mov_b32_e32 v143, v173
	v_mad_i32_i24 v145, v1, s52, v145
	v_mov_b32_e32 v131, v173
	v_lshlrev_b32_e32 v165, 2, v9
	v_lshl_add_u64 v[4:5], v[4:5], 0, v[142:143]
	v_lshl_add_u64 v[0:1], v[144:145], 0, v[130:131]
	v_mov_b32_e32 v133, v173
	v_or_b32_e32 v166, 3, v165
	global_load_dwordx4 v[36:39], v[4:5], off
	global_load_dwordx4 v[40:43], v[0:1], off offset:-96
	v_lshl_add_u64 v[0:1], v[140:141], 0, v[132:133]
	global_load_dword v131, v[0:1], off offset:-192
	v_min_u32_e32 v0, 4, v166
	v_lshl_add_u32 v6, v0, 6, v201
	v_add_u32_e32 v0, v6, v122
	v_max_i32_e32 v172, 0, v0
	v_lshl_add_u64 v[0:1], v[134:135], 0, v[172:173]
	v_lshlrev_b64 v[0:1], 11, v[0:1]
	v_lshl_add_u64 v[0:1], s[70:71], 0, v[0:1]
	v_add_u32_e32 v4, v6, v126
	v_lshl_add_u64 v[0:1], v[0:1], 0, v[2:3]
	v_max_i32_e32 v4, 0, v4
	v_lshl_add_u64 v[0:1], v[0:1], 0, v[142:143]
	v_lshlrev_b32_e32 v172, 1, v4
	v_lshl_add_u64 v[4:5], v[144:145], 0, v[172:173]
	global_load_dwordx4 v[44:47], v[0:1], off
	global_load_dwordx4 v[48:51], v[4:5], off
	v_add_u32_e32 v0, v6, v154
	v_max_i32_e32 v0, 0, v0
	v_lshlrev_b32_e32 v172, 2, v0
	v_lshl_add_u64 v[0:1], v[140:141], 0, v[172:173]
	global_load_dword v167, v[0:1], off
	v_min_u32_e32 v0, 5, v166
	v_lshl_add_u32 v6, v0, 6, v201
	v_add_u32_e32 v0, v6, v122
	v_max_i32_e32 v172, 0, v0
	v_lshl_add_u64 v[0:1], v[134:135], 0, v[172:173]
	v_lshlrev_b64 v[0:1], 11, v[0:1]
	v_lshl_add_u64 v[0:1], s[70:71], 0, v[0:1]
	v_add_u32_e32 v4, v6, v126
	v_lshl_add_u64 v[0:1], v[0:1], 0, v[2:3]
	v_max_i32_e32 v4, 0, v4
	v_lshl_add_u64 v[0:1], v[0:1], 0, v[142:143]
	v_lshlrev_b32_e32 v172, 1, v4
	v_lshl_add_u64 v[4:5], v[144:145], 0, v[172:173]
	global_load_dwordx4 v[52:55], v[0:1], off
	global_load_dwordx4 v[56:59], v[4:5], off
	v_add_u32_e32 v0, v6, v154
	v_max_i32_e32 v0, 0, v0
	v_lshlrev_b32_e32 v172, 2, v0
	v_lshl_add_u64 v[0:1], v[140:141], 0, v[172:173]
	global_load_dword v169, v[0:1], off
	v_sub_u32_e32 v0, 0, v8
	v_or_b32_e32 v1, v10, v155
	v_lshl_add_u64 v[146:147], v[128:129], 0, v[2:3]
	v_lshlrev_b32_e32 v0, 8, v0
	v_mov_b32_e32 v2, v173
	v_mov_b32_e32 v3, v173
	v_add_u32_e32 v133, s85, v1
	v_sub_u32_e32 v168, 0, v0
	v_mov_b32_e32 v172, v173
	v_mov_b32_e32 v0, v173
	v_mov_b32_e32 v1, v173
	v_mov_b64_e32 v[6:7], v[2:3]
	v_mov_b64_e32 v[10:11], v[2:3]
	v_mov_b64_e32 v[14:15], v[2:3]
	v_mov_b64_e32 v[18:19], v[2:3]
	v_mov_b64_e32 v[62:63], v[2:3]
	v_mov_b64_e32 v[66:67], v[2:3]
	v_mov_b64_e32 v[70:71], v[2:3]
	s_mov_b32 s60, s87
	s_mov_b32 s84, 0
	v_or_b32_e32 v143, 16, v133
	v_mov_b32_e32 v148, 0xff800000
	s_mov_b64 s[34:35], 0
	v_mov_b32_e32 v170, 0
	s_mov_b32 s87, 0
	v_mov_b64_e32 v[4:5], v[0:1]
	v_mov_b64_e32 v[8:9], v[0:1]
	v_mov_b64_e32 v[12:13], v[0:1]
	v_mov_b64_e32 v[16:17], v[0:1]
	v_mov_b64_e32 v[60:61], v[0:1]
	v_mov_b64_e32 v[64:65], v[0:1]
	v_mov_b64_e32 v[68:69], v[0:1]
	v_mov_b64_e32 v[136:137], v[172:173]
	v_mov_b32_e32 v149, 0xff800000
	v_min_u32_e32 v228, 6, v166
	v_lshl_add_u32 v234, v228, 6, v201
	v_add_u32_e32 v228, v234, v122
	v_add_u32_e32 v230, v234, v126
	v_max_i32_e32 v172, 0, v228
	v_max_i32_e32 v230, 0, v230
	v_lshl_add_u64 v[228:229], v[134:135], 0, v[172:173]
	v_lshlrev_b32_e32 v172, 1, v230
	v_add_u32_e32 v234, v234, v154
	v_lshlrev_b64 v[228:229], 11, v[228:229]
	v_lshl_add_u64 v[230:231], v[144:145], 0, v[172:173]
	v_max_i32_e32 v172, 0, v234
	v_lshl_add_u64 v[228:229], v[146:147], 0, v[228:229]
	v_lshl_add_u64 v[232:233], v[172:173], 2, v[140:141]
	v_mov_b32_e32 v172, v173
	s_branch .LBB0_798
